# attention hot loops: K/V LDS fragments read up front, PV in q-major order with next P-fragment exp/cvt placed in MFMA gaps
# speedup vs baseline: 1.0169x; 1.0169x over previous
; #define MFMA32(a, b, c) __builtin_amdgcn_mfma_f32_32x32x16_bf16((a), (b), (c), 0, 0, 0)
; DI unsigned pack2(float a, float b) { f32x2_t v = {a, b}; return __builtin_bit_cast(unsigned, __builtin_convertvector(v, bf16x2_t)); }
; template <int DK, int DV>
; DI void attn_map(f32x16 (&O)[DV / 32], float& lsum, const u16* qrow, const u16* K1, int ldk1, const u16* K2, int ldk2, const u16* Vt, int nkeys, char* smem) {
;     ...
;     bf16x8 pf[4];
; #pragma unroll
;     for (int j = 0; j < 2; ++j)
; #pragma unroll
;       for (int st = 0; st < 2; ++st) {
;         u32x4 pk;
;         pk.x = pack2(__builtin_amdgcn_exp2f(s[j][8 * st + 0]), __builtin_amdgcn_exp2f(s[j][8 * st + 1]));
;         pk.y = pack2(__builtin_amdgcn_exp2f(s[j][8 * st + 2]), __builtin_amdgcn_exp2f(s[j][8 * st + 3]));
;         pk.z = pack2(__builtin_amdgcn_exp2f(s[j][8 * st + 4]), __builtin_amdgcn_exp2f(s[j][8 * st + 5]));
;         pk.w = pack2(__builtin_amdgcn_exp2f(s[j][8 * st + 6]), __builtin_amdgcn_exp2f(s[j][8 * st + 7]));
;         pf[j * 2 + st] = __builtin_bit_cast(bf16x8, pk);
;       }
;     __builtin_amdgcn_s_setprio(1);
; #pragma unroll
;     for (int q = 0; q < 4; ++q) lacc = MFMA32(ones, pf[q], lacc);
; #pragma unroll
;     for (int dd = 0; dd < DV / 32; ++dd) {
; #pragma unroll
;       for (int q = 0; q < 4; ++q) {
;         bf16x8 vv = *(const bf16x8*)(Vs + (dd * 32 + r) * VST + q * 16 + 8 * h);
;         O[dd] = MFMA32(vv, pf[q], O[dd]);
;       }
;     }
;     {
;       constexpr int NPV = (DV / 32) * 4;
;       __builtin_amdgcn_sched_group_barrier(0x100, 2, 0);
; #pragma unroll
;       for (int q = 0; q < NPV - 2; ++q) { __builtin_amdgcn_sched_group_barrier(0x008, 1, 0); __builtin_amdgcn_sched_group_barrier(0x100, 1, 0); }
;       __builtin_amdgcn_sched_group_barrier(0x008, 6, 0);
;     }
;     __builtin_amdgcn_s_setprio(0);
.LBB0_381:
	s_add_i32 s10, s10, 64
	v_exp_f32_e32 v96, v96
	v_exp_f32_e32 v97, v97
	v_exp_f32_e32 v98, v98
	v_exp_f32_e32 v99, v99
	v_exp_f32_e32 v100, v100
	v_exp_f32_e32 v101, v101
	v_exp_f32_e32 v102, v102
	v_exp_f32_e32 v103, v103
	v_cvt_pk_bf16_f32 v96, v96, v97
	v_cvt_pk_bf16_f32 v97, v98, v99
	v_cvt_pk_bf16_f32 v98, v100, v101
	v_cvt_pk_bf16_f32 v99, v102, v103
	v_mov_b64_e32 v[232:233], s[48:49]
	v_mov_b64_e32 v[234:235], s[50:51]
	s_setprio 1
	s_waitcnt lgkmcnt(0)
	v_mfma_f32_32x32x16_bf16 v[48:63], v[200:203], v[96:99], v[48:63]
	ds_read_b128 v[200:203], v168 offset:9280
	v_exp_f32_e32 v100, v104
	v_exp_f32_e32 v101, v105
	v_mfma_f32_32x32x16_bf16 v[32:47], v[204:207], v[96:99], v[32:47]
	ds_read_b128 v[204:207], v168 offset:13888
	v_cvt_pk_bf16_f32 v100, v100, v101
	v_exp_f32_e32 v102, v106
	v_exp_f32_e32 v103, v107
	v_mfma_f32_32x32x16_bf16 v[64:79], v[208:211], v[96:99], v[64:79]
	ds_read_b128 v[208:211], v168 offset:18496
	v_cvt_pk_bf16_f32 v101, v102, v103
	v_exp_f32_e32 v104, v108
	v_exp_f32_e32 v105, v109
	v_exp_f32_e32 v106, v110
	v_mfma_f32_32x32x16_bf16 v[80:95], v[212:215], v[96:99], v[80:95]
	v_exp_f32_e32 v107, v111
	v_cvt_pk_bf16_f32 v102, v104, v105
	v_cvt_pk_bf16_f32 v103, v106, v107
	ds_read_b128 v[212:215], v168 offset:23104
	v_mfma_f32_32x32x16_bf16 v[0:15], v[232:235], v[96:99], v[0:15]
	v_mfma_f32_32x32x16_bf16 v[48:63], v[216:219], v[100:103], v[48:63]
	ds_read_b128 v[216:219], v168 offset:9312
	v_exp_f32_e32 v104, v112
	v_exp_f32_e32 v105, v113
	v_mfma_f32_32x32x16_bf16 v[32:47], v[220:223], v[100:103], v[32:47]
	ds_read_b128 v[220:223], v168 offset:13920
	v_cvt_pk_bf16_f32 v104, v104, v105
	v_exp_f32_e32 v106, v114
	v_exp_f32_e32 v107, v115
	v_mfma_f32_32x32x16_bf16 v[64:79], v[224:227], v[100:103], v[64:79]
	ds_read_b128 v[224:227], v168 offset:18528
	v_cvt_pk_bf16_f32 v105, v106, v107
	v_exp_f32_e32 v108, v116
	v_exp_f32_e32 v109, v117
	v_exp_f32_e32 v110, v118
	v_mfma_f32_32x32x16_bf16 v[80:95], v[228:231], v[100:103], v[80:95]
	v_exp_f32_e32 v111, v119
	v_cvt_pk_bf16_f32 v106, v108, v109
	v_cvt_pk_bf16_f32 v107, v110, v111
	ds_read_b128 v[228:231], v168 offset:23136
	v_mfma_f32_32x32x16_bf16 v[0:15], v[232:235], v[100:103], v[0:15]
	s_waitcnt lgkmcnt(7)
	v_mfma_f32_32x32x16_bf16 v[48:63], v[200:203], v[104:107], v[48:63]
	v_exp_f32_e32 v108, v120
	v_exp_f32_e32 v109, v121
	s_waitcnt lgkmcnt(6)
	v_mfma_f32_32x32x16_bf16 v[32:47], v[204:207], v[104:107], v[32:47]
	v_cvt_pk_bf16_f32 v108, v108, v109
	v_exp_f32_e32 v110, v122
	v_exp_f32_e32 v111, v123
	s_waitcnt lgkmcnt(5)
	v_mfma_f32_32x32x16_bf16 v[64:79], v[208:211], v[104:107], v[64:79]
	v_cvt_pk_bf16_f32 v109, v110, v111
	v_exp_f32_e32 v112, v124
	v_exp_f32_e32 v113, v125
	v_exp_f32_e32 v114, v126
	s_waitcnt lgkmcnt(4)
	v_mfma_f32_32x32x16_bf16 v[80:95], v[212:215], v[104:107], v[80:95]
	v_exp_f32_e32 v115, v127
	v_cvt_pk_bf16_f32 v110, v112, v113
	v_cvt_pk_bf16_f32 v111, v114, v115
	s_nop 0
	v_mfma_f32_32x32x16_bf16 v[0:15], v[232:235], v[104:107], v[0:15]
	s_waitcnt lgkmcnt(3)
	v_mfma_f32_32x32x16_bf16 v[48:63], v[216:219], v[108:111], v[48:63]
	s_waitcnt lgkmcnt(2)
	v_mfma_f32_32x32x16_bf16 v[32:47], v[220:223], v[108:111], v[32:47]
	s_waitcnt lgkmcnt(1)
	v_mfma_f32_32x32x16_bf16 v[64:79], v[224:227], v[108:111], v[64:79]
	s_waitcnt lgkmcnt(0)
	v_mfma_f32_32x32x16_bf16 v[80:95], v[228:231], v[108:111], v[80:95]
	v_mfma_f32_32x32x16_bf16 v[0:15], v[232:235], v[108:111], v[0:15]
	s_setprio 0
	v_lshl_add_u64 v[176:177], v[176:177], 0, s[56:57]
	v_lshl_add_u64 v[178:179], v[178:179], 0, s[56:57]
	v_lshl_add_u64 v[180:181], v[180:181], 0, s[56:57]
	v_lshl_add_u64 v[182:183], v[182:183], 0, s[56:57]
	v_lshl_add_u64 v[184:185], v[184:185], 0, s[58:59]
	s_andn2_b64 vcc, exec, s[8:9]
	v_lshl_add_u64 v[186:187], v[186:187], 0, s[58:59]
	s_cbranch_vccz .LBB0_386

; #define MFMA32(a, b, c) __builtin_amdgcn_mfma_f32_32x32x16_bf16((a), (b), (c), 0, 0, 0)
; DI float xmax32(float x) { auto t = __builtin_amdgcn_permlane32_swap(__float_as_uint(x), __float_as_uint(x), false, false); return fmaxf(__uint_as_float(t[0]), __uint_as_float(t[1])); }
; template <int DK, int DV>
; DI void attn_map(f32x16 (&O)[DV / 32], float& lsum, const u16* qrow, const u16* K1, int ldk1, const u16* K2, int ldk2, const u16* Vt, int nkeys, char* smem) {
;     ...
;     f32x16 s[2];
;     __builtin_amdgcn_s_setprio(1);
; #pragma unroll
;     for (int j = 0; j < 2; ++j) {
; #pragma unroll
;       for (int ks = 0; ks < DK / 16; ++ks) {
;         bf16x8 kf = *(const bf16x8*)(Ks + (j * 32 + r) * KST + ks * 16 + 8 * h);
;         s[j] = (ks == 0) ? MFMA32(kf, qf[ks], negm) : MFMA32(kf, qf[ks], s[j]);
;       }
;     }
;     {
;       constexpr int NQK = 2 * (DK / 16);
;       __builtin_amdgcn_sched_group_barrier(0x100, 2, 0);
; #pragma unroll
;       for (int q = 0; q < NQK - 2; ++q) { __builtin_amdgcn_sched_group_barrier(0x008, 1, 0); __builtin_amdgcn_sched_group_barrier(0x100, 1, 0); }
;       __builtin_amdgcn_sched_group_barrier(0x008, 2, 0);
;     }
;     __builtin_amdgcn_s_setprio(0);
;     float mx0 = fmaxf(fmaxf(s[0][0], s[0][1]), s[0][2]), mx1 = fmaxf(fmaxf(s[1][0], s[1][1]), s[1][2]);
; #pragma unroll
;     for (int i = 3; i < 15; i += 2) { mx0 = fmaxf(fmaxf(mx0, s[0][i]), s[0][i + 1]); mx1 = fmaxf(fmaxf(mx1, s[1][i]), s[1][i + 1]); }
;     float mx = fmaxf(fmaxf(mx0, mx1), fmaxf(s[0][15], s[1][15]));
;     mx = xmax32(mx);
;     const bool first = (k0 == 0);
;     if (first || __any(mx > 6.f)) {
;       float dl = first ? mx : fmaxf(mx, 0.f);
;       float alpha = __builtin_amdgcn_exp2f(-dl);
; #pragma unroll
;       for (int i = 0; i < 16; ++i) { negm[i] -= dl; lacc[i] *= alpha; }
; #pragma unroll
;       for (int dd = 0; dd < DV / 32; ++dd)
; #pragma unroll
;         for (int i = 0; i < 16; ++i) O[dd][i] *= alpha;
; #pragma unroll
;       for (int j = 0; j < 2; ++j)
; #pragma unroll
;         for (int i = 0; i < 16; ++i) s[j][i] -= dl;
;     }
.LBB0_384:
	s_setprio 1
	ds_read_b128 v[200:203], v168
	ds_read_b128 v[204:207], v168 offset:32
	ds_read_b128 v[208:211], v168 offset:64
	ds_read_b128 v[212:215], v168 offset:96
	ds_read_b128 v[216:219], v168 offset:4608
	ds_read_b128 v[220:223], v168 offset:4640
	ds_read_b128 v[224:227], v168 offset:4672
	ds_read_b128 v[228:231], v168 offset:4704
	s_waitcnt lgkmcnt(7)
	v_mfma_f32_32x32x16_bf16 v[96:111], v[200:203], v[128:131], v[16:31]
	s_waitcnt lgkmcnt(6)
	v_mfma_f32_32x32x16_bf16 v[96:111], v[204:207], v[132:135], v[96:111]
	s_waitcnt lgkmcnt(5)
	v_mfma_f32_32x32x16_bf16 v[96:111], v[208:211], v[136:139], v[96:111]
	s_waitcnt lgkmcnt(4)
	v_mfma_f32_32x32x16_bf16 v[96:111], v[212:215], v[140:143], v[96:111]
	s_waitcnt lgkmcnt(3)
	v_mfma_f32_32x32x16_bf16 v[112:127], v[216:219], v[128:131], v[16:31]
	s_waitcnt lgkmcnt(2)
	v_mfma_f32_32x32x16_bf16 v[112:127], v[220:223], v[132:135], v[112:127]
	s_waitcnt lgkmcnt(1)
	v_mfma_f32_32x32x16_bf16 v[112:127], v[224:227], v[136:139], v[112:127]
	s_waitcnt lgkmcnt(0)
	v_mfma_f32_32x32x16_bf16 v[112:127], v[228:231], v[140:143], v[112:127]
	s_setprio 0
	ds_read_b128 v[200:203], v168 offset:9216
	ds_read_b128 v[204:207], v168 offset:13824
	ds_read_b128 v[208:211], v168 offset:18432
	ds_read_b128 v[212:215], v168 offset:23040
	ds_read_b128 v[216:219], v168 offset:9248
	ds_read_b128 v[220:223], v168 offset:13856
	ds_read_b128 v[224:227], v168 offset:18464
	ds_read_b128 v[228:231], v168 offset:23072
	s_nop 0
	v_max3_f32 v194, v96, v97, v98
	s_nop 8
	v_max3_f32 v195, v112, v113, v114
	v_max3_f32 v194, v194, v99, v100
	v_max3_f32 v195, v195, v115, v116
	v_max3_f32 v194, v194, v101, v102
	v_max3_f32 v195, v195, v117, v118
	v_max3_f32 v194, v194, v103, v104
	v_max3_f32 v195, v195, v119, v120
	v_max3_f32 v194, v194, v105, v106
	v_max3_f32 v195, v195, v121, v122
	v_max3_f32 v194, v194, v107, v108
	v_max3_f32 v195, v195, v123, v124
	v_max_f32_e32 v196, v127, v127
	v_max_f32_e32 v197, v111, v111
	v_max3_f32 v194, v194, v109, v110
	v_max3_f32 v195, v195, v125, v126
	v_max_f32_e32 v196, v197, v196
	v_max3_f32 v194, v194, v195, v196
	v_mov_b32_e32 v195, v194
	s_nop 1
	v_permlane32_swap_b32_e32 v194, v195
	v_max_f32_e32 v195, v195, v195
	v_max_f32_e32 v194, v194, v194
	v_max_f32_e32 v194, v194, v195
	v_cmp_lt_f32_e32 vcc, s45, v194
	s_cbranch_vccz .LBB0_381
	v_max_f32_e32 v194, v194, v194
	v_max_f32_e32 v195, 0, v194
	v_exp_f32_e64 v194, -v195
	v_sub_f32_e32 v31, v31, v195
	v_sub_f32_e32 v30, v30, v195
	v_sub_f32_e32 v29, v29, v195
	v_pk_mul_f32 v[62:63], v[62:63], v[194:195] op_sel_hi:[1,0]
	v_pk_mul_f32 v[60:61], v[60:61], v[194:195] op_sel_hi:[1,0]
	v_pk_mul_f32 v[58:59], v[58:59], v[194:195] op_sel_hi:[1,0]
	v_pk_mul_f32 v[56:57], v[56:57], v[194:195] op_sel_hi:[1,0]
	v_pk_mul_f32 v[54:55], v[54:55], v[194:195] op_sel_hi:[1,0]
	v_pk_mul_f32 v[52:53], v[52:53], v[194:195] op_sel_hi:[1,0]
	v_pk_mul_f32 v[50:51], v[50:51], v[194:195] op_sel_hi:[1,0]
	v_pk_mul_f32 v[48:49], v[48:49], v[194:195] op_sel_hi:[1,0]
	v_pk_mul_f32 v[46:47], v[46:47], v[194:195] op_sel_hi:[1,0]
	v_pk_mul_f32 v[44:45], v[44:45], v[194:195] op_sel_hi:[1,0]
	v_pk_mul_f32 v[42:43], v[42:43], v[194:195] op_sel_hi:[1,0]
	v_pk_mul_f32 v[40:41], v[40:41], v[194:195] op_sel_hi:[1,0]
	v_pk_mul_f32 v[38:39], v[38:39], v[194:195] op_sel_hi:[1,0]
	v_pk_mul_f32 v[36:37], v[36:37], v[194:195] op_sel_hi:[1,0]
	v_pk_mul_f32 v[34:35], v[34:35], v[194:195] op_sel_hi:[1,0]
	v_pk_mul_f32 v[32:33], v[32:33], v[194:195] op_sel_hi:[1,0]
	v_pk_mul_f32 v[78:79], v[78:79], v[194:195] op_sel_hi:[1,0]
	v_pk_mul_f32 v[76:77], v[76:77], v[194:195] op_sel_hi:[1,0]
	v_pk_mul_f32 v[74:75], v[74:75], v[194:195] op_sel_hi:[1,0]
	v_pk_mul_f32 v[72:73], v[72:73], v[194:195] op_sel_hi:[1,0]
	v_pk_mul_f32 v[70:71], v[70:71], v[194:195] op_sel_hi:[1,0]
	v_pk_mul_f32 v[68:69], v[68:69], v[194:195] op_sel_hi:[1,0]
	v_pk_mul_f32 v[66:67], v[66:67], v[194:195] op_sel_hi:[1,0]
	v_pk_mul_f32 v[64:65], v[64:65], v[194:195] op_sel_hi:[1,0]
	v_pk_mul_f32 v[94:95], v[94:95], v[194:195] op_sel_hi:[1,0]
	v_pk_mul_f32 v[92:93], v[92:93], v[194:195] op_sel_hi:[1,0]
	v_pk_mul_f32 v[90:91], v[90:91], v[194:195] op_sel_hi:[1,0]
	v_pk_mul_f32 v[88:89], v[88:89], v[194:195] op_sel_hi:[1,0]
	v_pk_mul_f32 v[86:87], v[86:87], v[194:195] op_sel_hi:[1,0]
	v_pk_mul_f32 v[84:85], v[84:85], v[194:195] op_sel_hi:[1,0]
	v_pk_mul_f32 v[82:83], v[82:83], v[194:195] op_sel_hi:[1,0]
	v_pk_mul_f32 v[80:81], v[80:81], v[194:195] op_sel_hi:[1,0]
	v_sub_f32_e32 v28, v28, v195
	v_sub_f32_e32 v27, v27, v195
	v_sub_f32_e32 v26, v26, v195
	v_sub_f32_e32 v25, v25, v195
	v_sub_f32_e32 v24, v24, v195
	v_sub_f32_e32 v23, v23, v195
	v_sub_f32_e32 v22, v22, v195
	v_sub_f32_e32 v21, v21, v195
	v_sub_f32_e32 v20, v20, v195
	v_sub_f32_e32 v19, v19, v195
	v_sub_f32_e32 v18, v18, v195
	v_sub_f32_e32 v17, v17, v195
	v_sub_f32_e32 v16, v16, v195
	v_sub_f32_e32 v96, v96, v195
	v_sub_f32_e32 v97, v97, v195
	v_sub_f32_e32 v98, v98, v195
	v_sub_f32_e32 v99, v99, v195
	v_sub_f32_e32 v100, v100, v195
	v_sub_f32_e32 v101, v101, v195
	v_sub_f32_e32 v102, v102, v195
	v_sub_f32_e32 v103, v103, v195
	v_sub_f32_e32 v104, v104, v195
	v_sub_f32_e32 v105, v105, v195
	v_sub_f32_e32 v106, v106, v195
	v_sub_f32_e32 v107, v107, v195
	v_sub_f32_e32 v108, v108, v195
	v_sub_f32_e32 v109, v109, v195
	v_sub_f32_e32 v110, v110, v195
	v_sub_f32_e32 v111, v111, v195
	v_sub_f32_e32 v112, v112, v195
	v_sub_f32_e32 v113, v113, v195
	v_sub_f32_e32 v114, v114, v195
	v_sub_f32_e32 v115, v115, v195
	v_sub_f32_e32 v116, v116, v195
	v_sub_f32_e32 v117, v117, v195
	v_sub_f32_e32 v118, v118, v195
	v_sub_f32_e32 v119, v119, v195
	v_sub_f32_e32 v120, v120, v195
	v_sub_f32_e32 v121, v121, v195
	v_sub_f32_e32 v122, v122, v195
	v_sub_f32_e32 v123, v123, v195
	v_sub_f32_e32 v124, v124, v195
	v_sub_f32_e32 v125, v125, v195
	v_sub_f32_e32 v126, v126, v195
	v_sub_f32_e32 v127, v127, v195
	v_pk_mul_f32 v[14:15], v[14:15], v[194:195] op_sel_hi:[1,0]
	v_pk_mul_f32 v[12:13], v[12:13], v[194:195] op_sel_hi:[1,0]
	v_pk_mul_f32 v[10:11], v[10:11], v[194:195] op_sel_hi:[1,0]
	v_pk_mul_f32 v[8:9], v[8:9], v[194:195] op_sel_hi:[1,0]
	v_pk_mul_f32 v[6:7], v[6:7], v[194:195] op_sel_hi:[1,0]
	v_pk_mul_f32 v[4:5], v[4:5], v[194:195] op_sel_hi:[1,0]
	v_pk_mul_f32 v[2:3], v[2:3], v[194:195] op_sel_hi:[1,0]
	v_pk_mul_f32 v[0:1], v[0:1], v[194:195] op_sel_hi:[1,0]
	s_branch .LBB0_381

; #define MFMA32(a, b, c) __builtin_amdgcn_mfma_f32_32x32x16_bf16((a), (b), (c), 0, 0, 0)
; DI unsigned pack2(float a, float b) { f32x2_t v = {a, b}; return __builtin_bit_cast(unsigned, __builtin_convertvector(v, bf16x2_t)); }
; template <int DK, int DV>
; DI void attn_map(f32x16 (&O)[DV / 32], float& lsum, const u16* qrow, const u16* K1, int ldk1, const u16* K2, int ldk2, const u16* Vt, int nkeys, char* smem) {
;     ...
;     bf16x8 pf[4];
; #pragma unroll
;     for (int j = 0; j < 2; ++j)
; #pragma unroll
;       for (int st = 0; st < 2; ++st) {
;         u32x4 pk;
;         pk.x = pack2(__builtin_amdgcn_exp2f(s[j][8 * st + 0]), __builtin_amdgcn_exp2f(s[j][8 * st + 1]));
;         pk.y = pack2(__builtin_amdgcn_exp2f(s[j][8 * st + 2]), __builtin_amdgcn_exp2f(s[j][8 * st + 3]));
;         pk.z = pack2(__builtin_amdgcn_exp2f(s[j][8 * st + 4]), __builtin_amdgcn_exp2f(s[j][8 * st + 5]));
;         pk.w = pack2(__builtin_amdgcn_exp2f(s[j][8 * st + 6]), __builtin_amdgcn_exp2f(s[j][8 * st + 7]));
;         pf[j * 2 + st] = __builtin_bit_cast(bf16x8, pk);
;       }
;     __builtin_amdgcn_s_setprio(1);
; #pragma unroll
;     for (int q = 0; q < 4; ++q) lacc = MFMA32(ones, pf[q], lacc);
; #pragma unroll
;     for (int dd = 0; dd < DV / 32; ++dd) {
; #pragma unroll
;       for (int q = 0; q < 4; ++q) {
;         bf16x8 vv = *(const bf16x8*)(Vs + (dd * 32 + r) * VST + q * 16 + 8 * h);
;         O[dd] = MFMA32(vv, pf[q], O[dd]);
;       }
;     }
;     {
;       constexpr int NPV = (DV / 32) * 4;
;       __builtin_amdgcn_sched_group_barrier(0x100, 2, 0);
; #pragma unroll
;       for (int q = 0; q < NPV - 2; ++q) { __builtin_amdgcn_sched_group_barrier(0x008, 1, 0); __builtin_amdgcn_sched_group_barrier(0x100, 1, 0); }
;       __builtin_amdgcn_sched_group_barrier(0x008, 6, 0);
;     }
;     __builtin_amdgcn_s_setprio(0);
.LBB0_403:
	s_add_i32 s10, s10, 64
	v_exp_f32_e32 v96, v96
	v_exp_f32_e32 v97, v97
	v_exp_f32_e32 v98, v98
	v_exp_f32_e32 v99, v99
	v_exp_f32_e32 v100, v100
	v_exp_f32_e32 v101, v101
	v_exp_f32_e32 v102, v102
	v_exp_f32_e32 v103, v103
	v_cvt_pk_bf16_f32 v96, v96, v97
	v_cvt_pk_bf16_f32 v97, v98, v99
	v_cvt_pk_bf16_f32 v98, v100, v101
	v_cvt_pk_bf16_f32 v99, v102, v103
	v_mov_b64_e32 v[232:233], s[48:49]
	v_mov_b64_e32 v[234:235], s[50:51]
	s_setprio 1
	s_waitcnt lgkmcnt(0)
	v_mfma_f32_32x32x16_bf16 v[48:63], v[200:203], v[96:99], v[48:63]
	ds_read_b128 v[200:203], v195 offset:9280
	v_exp_f32_e32 v100, v104
	v_exp_f32_e32 v101, v105
	v_mfma_f32_32x32x16_bf16 v[32:47], v[204:207], v[96:99], v[32:47]
	ds_read_b128 v[204:207], v195 offset:13888
	v_cvt_pk_bf16_f32 v100, v100, v101
	v_exp_f32_e32 v102, v106
	v_exp_f32_e32 v103, v107
	v_mfma_f32_32x32x16_bf16 v[16:31], v[208:211], v[96:99], v[16:31]
	ds_read_b128 v[208:211], v195 offset:18496
	v_cvt_pk_bf16_f32 v101, v102, v103
	v_exp_f32_e32 v104, v108
	v_exp_f32_e32 v105, v109
	v_exp_f32_e32 v106, v110
	v_mfma_f32_32x32x16_bf16 v[0:15], v[212:215], v[96:99], v[0:15]
	v_exp_f32_e32 v107, v111
	v_cvt_pk_bf16_f32 v102, v104, v105
	v_cvt_pk_bf16_f32 v103, v106, v107
	ds_read_b128 v[212:215], v195 offset:23104
	v_mfma_f32_32x32x16_bf16 v[64:79], v[232:235], v[96:99], v[64:79]
	v_mfma_f32_32x32x16_bf16 v[48:63], v[216:219], v[100:103], v[48:63]
	ds_read_b128 v[216:219], v195 offset:9312
	v_exp_f32_e32 v104, v112
	v_exp_f32_e32 v105, v113
	v_mfma_f32_32x32x16_bf16 v[32:47], v[220:223], v[100:103], v[32:47]
	ds_read_b128 v[220:223], v195 offset:13920
	v_cvt_pk_bf16_f32 v104, v104, v105
	v_exp_f32_e32 v106, v114
	v_exp_f32_e32 v107, v115
	v_mfma_f32_32x32x16_bf16 v[16:31], v[224:227], v[100:103], v[16:31]
	ds_read_b128 v[224:227], v195 offset:18528
	v_cvt_pk_bf16_f32 v105, v106, v107
	v_exp_f32_e32 v108, v116
	v_exp_f32_e32 v109, v117
	v_exp_f32_e32 v110, v118
	v_mfma_f32_32x32x16_bf16 v[0:15], v[228:231], v[100:103], v[0:15]
	v_exp_f32_e32 v111, v119
	v_cvt_pk_bf16_f32 v106, v108, v109
	v_cvt_pk_bf16_f32 v107, v110, v111
	ds_read_b128 v[228:231], v195 offset:23136
	v_mfma_f32_32x32x16_bf16 v[64:79], v[232:235], v[100:103], v[64:79]
	s_waitcnt lgkmcnt(7)
	v_mfma_f32_32x32x16_bf16 v[48:63], v[200:203], v[104:107], v[48:63]
	v_exp_f32_e32 v108, v120
	v_exp_f32_e32 v109, v121
	s_waitcnt lgkmcnt(6)
	v_mfma_f32_32x32x16_bf16 v[32:47], v[204:207], v[104:107], v[32:47]
	v_cvt_pk_bf16_f32 v108, v108, v109
	v_exp_f32_e32 v110, v122
	v_exp_f32_e32 v111, v123
	s_waitcnt lgkmcnt(5)
	v_mfma_f32_32x32x16_bf16 v[16:31], v[208:211], v[104:107], v[16:31]
	v_cvt_pk_bf16_f32 v109, v110, v111
	v_exp_f32_e32 v112, v124
	v_exp_f32_e32 v113, v125
	v_exp_f32_e32 v114, v126
	s_waitcnt lgkmcnt(4)
	v_mfma_f32_32x32x16_bf16 v[0:15], v[212:215], v[104:107], v[0:15]
	v_exp_f32_e32 v115, v127
	v_cvt_pk_bf16_f32 v110, v112, v113
	v_cvt_pk_bf16_f32 v111, v114, v115
	s_nop 0
	v_mfma_f32_32x32x16_bf16 v[64:79], v[232:235], v[104:107], v[64:79]
	s_waitcnt lgkmcnt(3)
	v_mfma_f32_32x32x16_bf16 v[48:63], v[216:219], v[108:111], v[48:63]
	s_waitcnt lgkmcnt(2)
	v_mfma_f32_32x32x16_bf16 v[32:47], v[220:223], v[108:111], v[32:47]
	s_waitcnt lgkmcnt(1)
	v_mfma_f32_32x32x16_bf16 v[16:31], v[224:227], v[108:111], v[16:31]
	s_waitcnt lgkmcnt(0)
	v_mfma_f32_32x32x16_bf16 v[0:15], v[228:231], v[108:111], v[0:15]
	v_mfma_f32_32x32x16_bf16 v[64:79], v[232:235], v[108:111], v[64:79]
	s_setprio 0
	v_lshl_add_u64 v[176:177], v[176:177], 0, s[56:57]
	v_lshl_add_u64 v[178:179], v[178:179], 0, s[56:57]
	v_lshl_add_u64 v[180:181], v[180:181], 0, s[56:57]
	v_lshl_add_u64 v[182:183], v[182:183], 0, s[56:57]
	v_lshl_add_u64 v[184:185], v[184:185], 0, s[58:59]
	s_andn2_b64 vcc, exec, s[6:7]
	v_lshl_add_u64 v[186:187], v[186:187], 0, s[58:59]
	s_cbranch_vccz .LBB0_408

; #define MFMA32(a, b, c) __builtin_amdgcn_mfma_f32_32x32x16_bf16((a), (b), (c), 0, 0, 0)
; DI float xmax32(float x) { auto t = __builtin_amdgcn_permlane32_swap(__float_as_uint(x), __float_as_uint(x), false, false); return fmaxf(__uint_as_float(t[0]), __uint_as_float(t[1])); }
; template <int DK, int DV>
; DI void attn_map(f32x16 (&O)[DV / 32], float& lsum, const u16* qrow, const u16* K1, int ldk1, const u16* K2, int ldk2, const u16* Vt, int nkeys, char* smem) {
;     ...
;     f32x16 s[2];
;     __builtin_amdgcn_s_setprio(1);
; #pragma unroll
;     for (int j = 0; j < 2; ++j) {
; #pragma unroll
;       for (int ks = 0; ks < DK / 16; ++ks) {
;         bf16x8 kf = *(const bf16x8*)(Ks + (j * 32 + r) * KST + ks * 16 + 8 * h);
;         s[j] = (ks == 0) ? MFMA32(kf, qf[ks], negm) : MFMA32(kf, qf[ks], s[j]);
;       }
;     }
;     {
;       constexpr int NQK = 2 * (DK / 16);
;       __builtin_amdgcn_sched_group_barrier(0x100, 2, 0);
; #pragma unroll
;       for (int q = 0; q < NQK - 2; ++q) { __builtin_amdgcn_sched_group_barrier(0x008, 1, 0); __builtin_amdgcn_sched_group_barrier(0x100, 1, 0); }
;       __builtin_amdgcn_sched_group_barrier(0x008, 2, 0);
;     }
;     __builtin_amdgcn_s_setprio(0);
;     float mx0 = fmaxf(fmaxf(s[0][0], s[0][1]), s[0][2]), mx1 = fmaxf(fmaxf(s[1][0], s[1][1]), s[1][2]);
; #pragma unroll
;     for (int i = 3; i < 15; i += 2) { mx0 = fmaxf(fmaxf(mx0, s[0][i]), s[0][i + 1]); mx1 = fmaxf(fmaxf(mx1, s[1][i]), s[1][i + 1]); }
;     float mx = fmaxf(fmaxf(mx0, mx1), fmaxf(s[0][15], s[1][15]));
;     mx = xmax32(mx);
;     const bool first = (k0 == 0);
;     if (first || __any(mx > 6.f)) {
;       float dl = first ? mx : fmaxf(mx, 0.f);
;       float alpha = __builtin_amdgcn_exp2f(-dl);
; #pragma unroll
;       for (int i = 0; i < 16; ++i) { negm[i] -= dl; lacc[i] *= alpha; }
; #pragma unroll
;       for (int dd = 0; dd < DV / 32; ++dd)
; #pragma unroll
;         for (int i = 0; i < 16; ++i) O[dd][i] *= alpha;
; #pragma unroll
;       for (int j = 0; j < 2; ++j)
; #pragma unroll
;         for (int i = 0; i < 16; ++i) s[j][i] -= dl;
;     }
.LBB0_406:
	s_setprio 1
	ds_read_b128 v[200:203], v195
	ds_read_b128 v[204:207], v195 offset:32
	ds_read_b128 v[208:211], v195 offset:64
	ds_read_b128 v[212:215], v195 offset:96
	ds_read_b128 v[216:219], v195 offset:4608
	ds_read_b128 v[220:223], v195 offset:4640
	ds_read_b128 v[224:227], v195 offset:4672
	ds_read_b128 v[228:231], v195 offset:4704
	s_waitcnt lgkmcnt(7)
	v_mfma_f32_32x32x16_bf16 v[96:111], v[200:203], v[128:131], v[80:95]
	s_waitcnt lgkmcnt(6)
	v_mfma_f32_32x32x16_bf16 v[96:111], v[204:207], v[132:135], v[96:111]
	s_waitcnt lgkmcnt(5)
	v_mfma_f32_32x32x16_bf16 v[96:111], v[208:211], v[136:139], v[96:111]
	s_waitcnt lgkmcnt(4)
	v_mfma_f32_32x32x16_bf16 v[96:111], v[212:215], v[140:143], v[96:111]
	s_waitcnt lgkmcnt(3)
	v_mfma_f32_32x32x16_bf16 v[112:127], v[216:219], v[128:131], v[80:95]
	s_waitcnt lgkmcnt(2)
	v_mfma_f32_32x32x16_bf16 v[112:127], v[220:223], v[132:135], v[112:127]
	s_waitcnt lgkmcnt(1)
	v_mfma_f32_32x32x16_bf16 v[112:127], v[224:227], v[136:139], v[112:127]
	s_waitcnt lgkmcnt(0)
	v_mfma_f32_32x32x16_bf16 v[112:127], v[228:231], v[140:143], v[112:127]
	s_setprio 0
	ds_read_b128 v[200:203], v195 offset:9216
	ds_read_b128 v[204:207], v195 offset:13824
	ds_read_b128 v[208:211], v195 offset:18432
	ds_read_b128 v[212:215], v195 offset:23040
	ds_read_b128 v[216:219], v195 offset:9248
	ds_read_b128 v[220:223], v195 offset:13856
	ds_read_b128 v[224:227], v195 offset:18464
	ds_read_b128 v[228:231], v195 offset:23072
	s_nop 0
	v_max3_f32 v196, v96, v97, v98
	s_nop 8
	v_max3_f32 v197, v112, v113, v114
	v_max3_f32 v196, v196, v99, v100
	v_max3_f32 v197, v197, v115, v116
	v_max3_f32 v196, v196, v101, v102
	v_max3_f32 v197, v197, v117, v118
	v_max3_f32 v196, v196, v103, v104
	v_max3_f32 v197, v197, v119, v120
	v_max3_f32 v196, v196, v105, v106
	v_max3_f32 v197, v197, v121, v122
	v_max3_f32 v196, v196, v107, v108
	v_max3_f32 v197, v197, v123, v124
	v_max_f32_e32 v198, v127, v127
	v_max_f32_e32 v199, v111, v111
	v_max3_f32 v196, v196, v109, v110
	v_max3_f32 v197, v197, v125, v126
	v_max_f32_e32 v198, v199, v198
	v_max3_f32 v196, v196, v197, v198
	v_mov_b32_e32 v197, v196
	s_nop 1
	v_permlane32_swap_b32_e32 v196, v197
	v_max_f32_e32 v197, v197, v197
	v_max_f32_e32 v196, v196, v196
	v_max_f32_e32 v196, v196, v197
	v_cmp_lt_f32_e32 vcc, s45, v196
	s_cbranch_vccz .LBB0_403
	v_max_f32_e32 v196, v196, v196
	v_max_f32_e32 v197, 0, v196
	v_exp_f32_e64 v196, -v197
	v_sub_f32_e32 v95, v95, v197
	v_sub_f32_e32 v94, v94, v197
	v_sub_f32_e32 v93, v93, v197
	v_pk_mul_f32 v[62:63], v[62:63], v[196:197] op_sel_hi:[1,0]
	v_pk_mul_f32 v[60:61], v[60:61], v[196:197] op_sel_hi:[1,0]
	v_pk_mul_f32 v[58:59], v[58:59], v[196:197] op_sel_hi:[1,0]
	v_pk_mul_f32 v[56:57], v[56:57], v[196:197] op_sel_hi:[1,0]
	v_pk_mul_f32 v[54:55], v[54:55], v[196:197] op_sel_hi:[1,0]
	v_pk_mul_f32 v[52:53], v[52:53], v[196:197] op_sel_hi:[1,0]
	v_pk_mul_f32 v[50:51], v[50:51], v[196:197] op_sel_hi:[1,0]
	v_pk_mul_f32 v[48:49], v[48:49], v[196:197] op_sel_hi:[1,0]
	v_pk_mul_f32 v[46:47], v[46:47], v[196:197] op_sel_hi:[1,0]
	v_pk_mul_f32 v[44:45], v[44:45], v[196:197] op_sel_hi:[1,0]
	v_pk_mul_f32 v[42:43], v[42:43], v[196:197] op_sel_hi:[1,0]
	v_pk_mul_f32 v[40:41], v[40:41], v[196:197] op_sel_hi:[1,0]
	v_pk_mul_f32 v[38:39], v[38:39], v[196:197] op_sel_hi:[1,0]
	v_pk_mul_f32 v[36:37], v[36:37], v[196:197] op_sel_hi:[1,0]
	v_pk_mul_f32 v[34:35], v[34:35], v[196:197] op_sel_hi:[1,0]
	v_pk_mul_f32 v[32:33], v[32:33], v[196:197] op_sel_hi:[1,0]
	v_pk_mul_f32 v[30:31], v[30:31], v[196:197] op_sel_hi:[1,0]
	v_pk_mul_f32 v[28:29], v[28:29], v[196:197] op_sel_hi:[1,0]
	v_pk_mul_f32 v[26:27], v[26:27], v[196:197] op_sel_hi:[1,0]
	v_pk_mul_f32 v[24:25], v[24:25], v[196:197] op_sel_hi:[1,0]
	v_pk_mul_f32 v[22:23], v[22:23], v[196:197] op_sel_hi:[1,0]
	v_pk_mul_f32 v[20:21], v[20:21], v[196:197] op_sel_hi:[1,0]
	v_pk_mul_f32 v[18:19], v[18:19], v[196:197] op_sel_hi:[1,0]
	v_pk_mul_f32 v[16:17], v[16:17], v[196:197] op_sel_hi:[1,0]
	v_pk_mul_f32 v[14:15], v[14:15], v[196:197] op_sel_hi:[1,0]
	v_pk_mul_f32 v[12:13], v[12:13], v[196:197] op_sel_hi:[1,0]
	v_pk_mul_f32 v[10:11], v[10:11], v[196:197] op_sel_hi:[1,0]
	v_pk_mul_f32 v[8:9], v[8:9], v[196:197] op_sel_hi:[1,0]
	v_pk_mul_f32 v[6:7], v[6:7], v[196:197] op_sel_hi:[1,0]
	v_pk_mul_f32 v[4:5], v[4:5], v[196:197] op_sel_hi:[1,0]
	v_pk_mul_f32 v[2:3], v[2:3], v[196:197] op_sel_hi:[1,0]
	v_pk_mul_f32 v[0:1], v[0:1], v[196:197] op_sel_hi:[1,0]
	v_sub_f32_e32 v92, v92, v197
	v_sub_f32_e32 v91, v91, v197
	v_sub_f32_e32 v90, v90, v197
	v_sub_f32_e32 v89, v89, v197
	v_sub_f32_e32 v88, v88, v197
	v_sub_f32_e32 v87, v87, v197
	v_sub_f32_e32 v86, v86, v197
	v_sub_f32_e32 v85, v85, v197
	v_sub_f32_e32 v84, v84, v197
	v_sub_f32_e32 v83, v83, v197
	v_sub_f32_e32 v82, v82, v197
	v_sub_f32_e32 v81, v81, v197
	v_sub_f32_e32 v80, v80, v197
	v_sub_f32_e32 v96, v96, v197
	v_sub_f32_e32 v97, v97, v197
	v_sub_f32_e32 v98, v98, v197
	v_sub_f32_e32 v99, v99, v197
	v_sub_f32_e32 v100, v100, v197
	v_sub_f32_e32 v101, v101, v197
	v_sub_f32_e32 v102, v102, v197
	v_sub_f32_e32 v103, v103, v197
	v_sub_f32_e32 v104, v104, v197
	v_sub_f32_e32 v105, v105, v197
	v_sub_f32_e32 v106, v106, v197
	v_sub_f32_e32 v107, v107, v197
	v_sub_f32_e32 v108, v108, v197
	v_sub_f32_e32 v109, v109, v197
	v_sub_f32_e32 v110, v110, v197
	v_sub_f32_e32 v111, v111, v197
	v_sub_f32_e32 v112, v112, v197
	v_sub_f32_e32 v113, v113, v197
	v_sub_f32_e32 v114, v114, v197
	v_sub_f32_e32 v115, v115, v197
	v_sub_f32_e32 v116, v116, v197
	v_sub_f32_e32 v117, v117, v197
	v_sub_f32_e32 v118, v118, v197
	v_sub_f32_e32 v119, v119, v197
	v_sub_f32_e32 v120, v120, v197
	v_sub_f32_e32 v121, v121, v197
	v_sub_f32_e32 v122, v122, v197
	v_sub_f32_e32 v123, v123, v197
	v_sub_f32_e32 v124, v124, v197
	v_sub_f32_e32 v125, v125, v197
	v_sub_f32_e32 v126, v126, v197
	v_sub_f32_e32 v127, v127, v197
	v_pk_mul_f32 v[78:79], v[78:79], v[196:197] op_sel_hi:[1,0]
	v_pk_mul_f32 v[76:77], v[76:77], v[196:197] op_sel_hi:[1,0]
	v_pk_mul_f32 v[74:75], v[74:75], v[196:197] op_sel_hi:[1,0]
	v_pk_mul_f32 v[72:73], v[72:73], v[196:197] op_sel_hi:[1,0]
	v_pk_mul_f32 v[70:71], v[70:71], v[196:197] op_sel_hi:[1,0]
	v_pk_mul_f32 v[68:69], v[68:69], v[196:197] op_sel_hi:[1,0]
	v_pk_mul_f32 v[66:67], v[66:67], v[196:197] op_sel_hi:[1,0]
	v_pk_mul_f32 v[64:65], v[64:65], v[196:197] op_sel_hi:[1,0]
	s_branch .LBB0_403

; #define MFMA32(a, b, c) __builtin_amdgcn_mfma_f32_32x32x16_bf16((a), (b), (c), 0, 0, 0)
; DI float xmax32(float x) { auto t = __builtin_amdgcn_permlane32_swap(__float_as_uint(x), __float_as_uint(x), false, false); return fmaxf(__uint_as_float(t[0]), __uint_as_float(t[1])); }
; template <int DK, int DV>
; DI void attn_map(f32x16 (&O)[DV / 32], float& lsum, const u16* qrow, const u16* K1, int ldk1, const u16* K2, int ldk2, const u16* Vt, int nkeys, char* smem) {
;     ...
;     f32x16 s[2];
;     __builtin_amdgcn_s_setprio(1);
; #pragma unroll
;     for (int j = 0; j < 2; ++j) {
; #pragma unroll
;       for (int ks = 0; ks < DK / 16; ++ks) {
;         bf16x8 kf = *(const bf16x8*)(Ks + (j * 32 + r) * KST + ks * 16 + 8 * h);
;         s[j] = (ks == 0) ? MFMA32(kf, qf[ks], negm) : MFMA32(kf, qf[ks], s[j]);
;       }
;     }
;     {
;       constexpr int NQK = 2 * (DK / 16);
;       __builtin_amdgcn_sched_group_barrier(0x100, 2, 0);
; #pragma unroll
;       for (int q = 0; q < NQK - 2; ++q) { __builtin_amdgcn_sched_group_barrier(0x008, 1, 0); __builtin_amdgcn_sched_group_barrier(0x100, 1, 0); }
;       __builtin_amdgcn_sched_group_barrier(0x008, 2, 0);
;     }
;     __builtin_amdgcn_s_setprio(0);
;     float mx0 = fmaxf(fmaxf(s[0][0], s[0][1]), s[0][2]), mx1 = fmaxf(fmaxf(s[1][0], s[1][1]), s[1][2]);
; #pragma unroll
;     for (int i = 3; i < 15; i += 2) { mx0 = fmaxf(fmaxf(mx0, s[0][i]), s[0][i + 1]); mx1 = fmaxf(fmaxf(mx1, s[1][i]), s[1][i + 1]); }
;     float mx = fmaxf(fmaxf(mx0, mx1), fmaxf(s[0][15], s[1][15]));
;     mx = xmax32(mx);
;     const bool first = (k0 == 0);
;     if (first || __any(mx > 6.f)) {
;       float dl = first ? mx : fmaxf(mx, 0.f);
;       float alpha = __builtin_amdgcn_exp2f(-dl);
; #pragma unroll
;       for (int i = 0; i < 16; ++i) { negm[i] -= dl; lacc[i] *= alpha; }
; #pragma unroll
;       for (int dd = 0; dd < DV / 32; ++dd)
; #pragma unroll
;         for (int i = 0; i < 16; ++i) O[dd][i] *= alpha;
; #pragma unroll
;       for (int j = 0; j < 2; ++j)
; #pragma unroll
;         for (int i = 0; i < 16; ++i) s[j][i] -= dl;
;     }
.LBB0_438:
	s_setprio 1
	ds_read_b128 v[190:193], v143
	ds_read_b128 v[194:197], v143 offset:32
	ds_read_b128 v[198:201], v143 offset:64
	ds_read_b128 v[202:205], v143 offset:96
	ds_read_b128 v[206:209], v143 offset:128
	ds_read_b128 v[210:213], v143 offset:160
	ds_read_b128 v[214:217], v143 offset:6656
	ds_read_b128 v[218:221], v143 offset:6688
	ds_read_b128 v[222:225], v143 offset:6720
	ds_read_b128 v[226:229], v143 offset:6752
	ds_read_b128 v[230:233], v143 offset:6784
	ds_read_b128 v[234:237], v143 offset:6816
	s_waitcnt lgkmcnt(11)
	v_mfma_f32_32x32x16_bf16 v[64:79], v[190:193], v[96:99], v[16:31]
	s_waitcnt lgkmcnt(10)
	v_mfma_f32_32x32x16_bf16 v[64:79], v[194:197], v[100:103], v[64:79]
	s_waitcnt lgkmcnt(9)
	v_mfma_f32_32x32x16_bf16 v[64:79], v[198:201], v[104:107], v[64:79]
	s_waitcnt lgkmcnt(8)
	v_mfma_f32_32x32x16_bf16 v[64:79], v[202:205], v[108:111], v[64:79]
	s_waitcnt lgkmcnt(7)
	v_mfma_f32_32x32x16_bf16 v[64:79], v[206:209], v[112:115], v[64:79]
	s_waitcnt lgkmcnt(6)
	v_mfma_f32_32x32x16_bf16 v[64:79], v[210:213], v[116:119], v[64:79]
	s_waitcnt lgkmcnt(5)
	v_mfma_f32_32x32x16_bf16 v[80:95], v[214:217], v[96:99], v[16:31]
	s_waitcnt lgkmcnt(4)
	v_mfma_f32_32x32x16_bf16 v[80:95], v[218:221], v[100:103], v[80:95]
	s_waitcnt lgkmcnt(3)
	v_mfma_f32_32x32x16_bf16 v[80:95], v[222:225], v[104:107], v[80:95]
	s_waitcnt lgkmcnt(2)
	v_mfma_f32_32x32x16_bf16 v[80:95], v[226:229], v[108:111], v[80:95]
	s_waitcnt lgkmcnt(1)
	v_mfma_f32_32x32x16_bf16 v[80:95], v[230:233], v[112:115], v[80:95]
	s_waitcnt lgkmcnt(0)
	v_mfma_f32_32x32x16_bf16 v[80:95], v[234:237], v[116:119], v[80:95]
	s_setprio 0
	ds_read_b128 v[190:193], v168 offset:13312
	ds_read_b128 v[194:197], v168 offset:17920
	ds_read_b128 v[198:201], v168 offset:13344
	ds_read_b128 v[202:205], v168 offset:17952
	ds_read_b128 v[206:209], v168 offset:13376
	ds_read_b128 v[210:213], v168 offset:17984
	ds_read_b128 v[214:217], v168 offset:13408
	ds_read_b128 v[218:221], v168 offset:18016
	v_max3_f32 v173, v64, v65, v66
	s_nop 9
	v_max3_f32 v174, v80, v81, v82
	v_max3_f32 v173, v173, v67, v68
	v_max3_f32 v174, v174, v83, v84
	v_max3_f32 v173, v173, v69, v70
	v_max3_f32 v174, v174, v85, v86
	v_max3_f32 v173, v173, v71, v72
	v_max3_f32 v174, v174, v87, v88
	v_max3_f32 v173, v173, v73, v74
	v_max3_f32 v174, v174, v89, v90
	v_max3_f32 v173, v173, v75, v76
	v_max3_f32 v174, v174, v91, v92
	v_max_f32_e32 v175, v95, v95
	v_max_f32_e32 v176, v79, v79
	v_max3_f32 v173, v173, v77, v78
	v_max3_f32 v174, v174, v93, v94
	v_max_f32_e32 v175, v176, v175
	v_max3_f32 v173, v173, v174, v175
	v_mov_b32_e32 v174, v173
	s_nop 1
	v_permlane32_swap_b32_e32 v173, v174
	v_max_f32_e32 v174, v174, v174
	v_max_f32_e32 v173, v173, v173
	v_max_f32_e32 v173, v173, v174
	v_cmp_lt_f32_e32 vcc, s45, v173
	s_cbranch_vccz .LBB0_440
	v_max_f32_e32 v173, v173, v173
	v_max_f32_e32 v173, 0, v173
	v_exp_f32_e64 v174, -v173
	v_sub_f32_e32 v31, v31, v173
	v_sub_f32_e32 v30, v30, v173
	v_sub_f32_e32 v29, v29, v173
	v_pk_mul_f32 v[62:63], v[62:63], v[174:175] op_sel_hi:[1,0]
	v_pk_mul_f32 v[60:61], v[60:61], v[174:175] op_sel_hi:[1,0]
	v_pk_mul_f32 v[58:59], v[58:59], v[174:175] op_sel_hi:[1,0]
	v_pk_mul_f32 v[56:57], v[56:57], v[174:175] op_sel_hi:[1,0]
	v_pk_mul_f32 v[54:55], v[54:55], v[174:175] op_sel_hi:[1,0]
	v_pk_mul_f32 v[52:53], v[52:53], v[174:175] op_sel_hi:[1,0]
	v_pk_mul_f32 v[50:51], v[50:51], v[174:175] op_sel_hi:[1,0]
	v_pk_mul_f32 v[48:49], v[48:49], v[174:175] op_sel_hi:[1,0]
	v_pk_mul_f32 v[46:47], v[46:47], v[174:175] op_sel_hi:[1,0]
	v_pk_mul_f32 v[44:45], v[44:45], v[174:175] op_sel_hi:[1,0]
	v_pk_mul_f32 v[42:43], v[42:43], v[174:175] op_sel_hi:[1,0]
	v_pk_mul_f32 v[40:41], v[40:41], v[174:175] op_sel_hi:[1,0]
	v_pk_mul_f32 v[38:39], v[38:39], v[174:175] op_sel_hi:[1,0]
	v_pk_mul_f32 v[36:37], v[36:37], v[174:175] op_sel_hi:[1,0]
	v_pk_mul_f32 v[34:35], v[34:35], v[174:175] op_sel_hi:[1,0]
	v_pk_mul_f32 v[32:33], v[32:33], v[174:175] op_sel_hi:[1,0]
	v_sub_f32_e32 v28, v28, v173
	v_sub_f32_e32 v27, v27, v173
	v_sub_f32_e32 v26, v26, v173
	v_sub_f32_e32 v25, v25, v173
	v_sub_f32_e32 v24, v24, v173
	v_sub_f32_e32 v23, v23, v173
	v_sub_f32_e32 v22, v22, v173
	v_sub_f32_e32 v21, v21, v173
	v_sub_f32_e32 v20, v20, v173
	v_sub_f32_e32 v19, v19, v173
	v_sub_f32_e32 v18, v18, v173
	v_sub_f32_e32 v17, v17, v173
	v_sub_f32_e32 v16, v16, v173
	v_sub_f32_e32 v64, v64, v173
	v_sub_f32_e32 v65, v65, v173
	v_sub_f32_e32 v66, v66, v173
	v_sub_f32_e32 v67, v67, v173
	v_sub_f32_e32 v68, v68, v173
	v_sub_f32_e32 v69, v69, v173
	v_sub_f32_e32 v70, v70, v173
	v_sub_f32_e32 v71, v71, v173
	v_sub_f32_e32 v72, v72, v173
	v_sub_f32_e32 v73, v73, v173
	v_sub_f32_e32 v74, v74, v173
	v_sub_f32_e32 v75, v75, v173
	v_sub_f32_e32 v76, v76, v173
	v_sub_f32_e32 v77, v77, v173
	v_sub_f32_e32 v78, v78, v173
	v_sub_f32_e32 v79, v79, v173
	v_sub_f32_e32 v80, v80, v173
	v_sub_f32_e32 v81, v81, v173
	v_sub_f32_e32 v82, v82, v173
	v_sub_f32_e32 v83, v83, v173
	v_sub_f32_e32 v84, v84, v173
	v_sub_f32_e32 v85, v85, v173
	v_sub_f32_e32 v86, v86, v173
	v_sub_f32_e32 v87, v87, v173
	v_sub_f32_e32 v88, v88, v173
	v_sub_f32_e32 v89, v89, v173
	v_sub_f32_e32 v90, v90, v173
	v_sub_f32_e32 v91, v91, v173
	v_sub_f32_e32 v92, v92, v173
	v_sub_f32_e32 v93, v93, v173
	v_sub_f32_e32 v94, v94, v173
	v_sub_f32_e32 v95, v95, v173
	v_pk_mul_f32 v[14:15], v[14:15], v[174:175] op_sel_hi:[1,0]
	v_pk_mul_f32 v[12:13], v[12:13], v[174:175] op_sel_hi:[1,0]
	v_pk_mul_f32 v[10:11], v[10:11], v[174:175] op_sel_hi:[1,0]
	v_pk_mul_f32 v[8:9], v[8:9], v[174:175] op_sel_hi:[1,0]
	v_pk_mul_f32 v[6:7], v[6:7], v[174:175] op_sel_hi:[1,0]
	v_pk_mul_f32 v[4:5], v[4:5], v[174:175] op_sel_hi:[1,0]
	v_pk_mul_f32 v[2:3], v[2:3], v[174:175] op_sel_hi:[1,0]
	v_pk_mul_f32 v[0:1], v[0:1], v[174:175] op_sel_hi:[1,0]
; #define MFMA32(a, b, c) __builtin_amdgcn_mfma_f32_32x32x16_bf16((a), (b), (c), 0, 0, 0)
; DI unsigned pack2(float a, float b) { f32x2_t v = {a, b}; return __builtin_bit_cast(unsigned, __builtin_convertvector(v, bf16x2_t)); }
; template <int DK, int DV>
; DI void attn_map(f32x16 (&O)[DV / 32], float& lsum, const u16* qrow, const u16* K1, int ldk1, const u16* K2, int ldk2, const u16* Vt, int nkeys, char* smem) {
;     ...
;     bf16x8 pf[4];
; #pragma unroll
;     for (int j = 0; j < 2; ++j)
; #pragma unroll
;       for (int st = 0; st < 2; ++st) {
;         u32x4 pk;
;         pk.x = pack2(__builtin_amdgcn_exp2f(s[j][8 * st + 0]), __builtin_amdgcn_exp2f(s[j][8 * st + 1]));
;         pk.y = pack2(__builtin_amdgcn_exp2f(s[j][8 * st + 2]), __builtin_amdgcn_exp2f(s[j][8 * st + 3]));
;         pk.z = pack2(__builtin_amdgcn_exp2f(s[j][8 * st + 4]), __builtin_amdgcn_exp2f(s[j][8 * st + 5]));
;         pk.w = pack2(__builtin_amdgcn_exp2f(s[j][8 * st + 6]), __builtin_amdgcn_exp2f(s[j][8 * st + 7]));
;         pf[j * 2 + st] = __builtin_bit_cast(bf16x8, pk);
;       }
;     __builtin_amdgcn_s_setprio(1);
; #pragma unroll
;     for (int q = 0; q < 4; ++q) lacc = MFMA32(ones, pf[q], lacc);
; #pragma unroll
;     for (int dd = 0; dd < DV / 32; ++dd) {
; #pragma unroll
;       for (int q = 0; q < 4; ++q) {
;         bf16x8 vv = *(const bf16x8*)(Vs + (dd * 32 + r) * VST + q * 16 + 8 * h);
;         O[dd] = MFMA32(vv, pf[q], O[dd]);
;       }
;     }
;     {
;       constexpr int NPV = (DV / 32) * 4;
;       __builtin_amdgcn_sched_group_barrier(0x100, 2, 0);
; #pragma unroll
;       for (int q = 0; q < NPV - 2; ++q) { __builtin_amdgcn_sched_group_barrier(0x008, 1, 0); __builtin_amdgcn_sched_group_barrier(0x100, 1, 0); }
;       __builtin_amdgcn_sched_group_barrier(0x008, 6, 0);
;     }
;     __builtin_amdgcn_s_setprio(0);
.LBB0_440:
	v_exp_f32_e32 v64, v64
	v_exp_f32_e32 v65, v65
	v_exp_f32_e32 v66, v66
	v_exp_f32_e32 v67, v67
	v_exp_f32_e32 v68, v68
	v_exp_f32_e32 v69, v69
	v_exp_f32_e32 v70, v70
	v_exp_f32_e32 v71, v71
	v_cvt_pk_bf16_f32 v64, v64, v65
	v_cvt_pk_bf16_f32 v65, v66, v67
	v_cvt_pk_bf16_f32 v66, v68, v69
	v_cvt_pk_bf16_f32 v67, v70, v71
	v_mov_b64_e32 v[184:185], s[48:49]
	v_mov_b64_e32 v[186:187], s[50:51]
	s_setprio 1
	s_waitcnt lgkmcnt(0)
	v_mfma_f32_32x32x16_bf16 v[48:63], v[190:193], v[64:67], v[48:63]
	v_exp_f32_e32 v68, v72
	v_exp_f32_e32 v69, v73
	v_exp_f32_e32 v70, v74
	v_exp_f32_e32 v71, v75
	v_mfma_f32_32x32x16_bf16 v[32:47], v[194:197], v[64:67], v[32:47]
	v_cvt_pk_bf16_f32 v68, v68, v69
	v_cvt_pk_bf16_f32 v69, v70, v71
	v_exp_f32_e32 v72, v76
	v_exp_f32_e32 v73, v77
	v_exp_f32_e32 v74, v78
	v_mfma_f32_32x32x16_bf16 v[0:15], v[184:187], v[64:67], v[0:15]
	v_exp_f32_e32 v75, v79
	v_cvt_pk_bf16_f32 v70, v72, v73
	v_cvt_pk_bf16_f32 v71, v74, v75
	s_nop 0
	s_nop 0
	v_mfma_f32_32x32x16_bf16 v[48:63], v[198:201], v[68:71], v[48:63]
	v_exp_f32_e32 v72, v80
	v_exp_f32_e32 v73, v81
	v_exp_f32_e32 v74, v82
	v_exp_f32_e32 v75, v83
	v_mfma_f32_32x32x16_bf16 v[32:47], v[202:205], v[68:71], v[32:47]
	v_cvt_pk_bf16_f32 v72, v72, v73
	v_cvt_pk_bf16_f32 v73, v74, v75
	v_exp_f32_e32 v76, v84
	v_exp_f32_e32 v77, v85
	v_exp_f32_e32 v78, v86
	v_mfma_f32_32x32x16_bf16 v[0:15], v[184:187], v[68:71], v[0:15]
	v_exp_f32_e32 v79, v87
	v_cvt_pk_bf16_f32 v74, v76, v77
	v_cvt_pk_bf16_f32 v75, v78, v79
	s_nop 0
	s_nop 0
	v_mfma_f32_32x32x16_bf16 v[48:63], v[206:209], v[72:75], v[48:63]
	v_exp_f32_e32 v76, v88
	v_exp_f32_e32 v77, v89
	v_exp_f32_e32 v78, v90
	v_exp_f32_e32 v79, v91
	v_mfma_f32_32x32x16_bf16 v[32:47], v[210:213], v[72:75], v[32:47]
	v_cvt_pk_bf16_f32 v76, v76, v77
	v_cvt_pk_bf16_f32 v77, v78, v79
	v_exp_f32_e32 v80, v92
	v_exp_f32_e32 v81, v93
	v_exp_f32_e32 v82, v94
	v_mfma_f32_32x32x16_bf16 v[0:15], v[184:187], v[72:75], v[0:15]
	v_exp_f32_e32 v83, v95
	v_cvt_pk_bf16_f32 v78, v80, v81
	v_cvt_pk_bf16_f32 v79, v82, v83
	s_nop 0
	s_nop 0
	v_mfma_f32_32x32x16_bf16 v[48:63], v[214:217], v[76:79], v[48:63]
	v_mfma_f32_32x32x16_bf16 v[32:47], v[218:221], v[76:79], v[32:47]
	v_mfma_f32_32x32x16_bf16 v[0:15], v[184:187], v[76:79], v[0:15]
	s_setprio 0
	v_lshl_add_u64 v[154:155], v[154:155], 0, s[56:57]
	s_andn2_b64 vcc, exec, s[8:9]
	v_lshl_add_u64 v[156:157], v[156:157], 0, s[56:57]
	s_cbranch_vccz .LBB0_442
	s_mov_b64 s[10:11], s[6:7]
	s_branch .LBB0_436

; #define MFMA32(a, b, c) __builtin_amdgcn_mfma_f32_32x32x16_bf16((a), (b), (c), 0, 0, 0)
; DI unsigned pack2(float a, float b) { f32x2_t v = {a, b}; return __builtin_bit_cast(unsigned, __builtin_convertvector(v, bf16x2_t)); }
; template <int DK, int DV>
; DI void attn_map(f32x16 (&O)[DV / 32], float& lsum, const u16* qrow, const u16* K1, int ldk1, const u16* K2, int ldk2, const u16* Vt, int nkeys, char* smem) {
;     ...
;     bf16x8 pf[4];
; #pragma unroll
;     for (int j = 0; j < 2; ++j)
; #pragma unroll
;       for (int st = 0; st < 2; ++st) {
;         u32x4 pk;
;         pk.x = pack2(__builtin_amdgcn_exp2f(s[j][8 * st + 0]), __builtin_amdgcn_exp2f(s[j][8 * st + 1]));
;         pk.y = pack2(__builtin_amdgcn_exp2f(s[j][8 * st + 2]), __builtin_amdgcn_exp2f(s[j][8 * st + 3]));
;         pk.z = pack2(__builtin_amdgcn_exp2f(s[j][8 * st + 4]), __builtin_amdgcn_exp2f(s[j][8 * st + 5]));
;         pk.w = pack2(__builtin_amdgcn_exp2f(s[j][8 * st + 6]), __builtin_amdgcn_exp2f(s[j][8 * st + 7]));
;         pf[j * 2 + st] = __builtin_bit_cast(bf16x8, pk);
;       }
;     __builtin_amdgcn_s_setprio(1);
; #pragma unroll
;     for (int q = 0; q < 4; ++q) lacc = MFMA32(ones, pf[q], lacc);
; #pragma unroll
;     for (int dd = 0; dd < DV / 32; ++dd) {
; #pragma unroll
;       for (int q = 0; q < 4; ++q) {
;         bf16x8 vv = *(const bf16x8*)(Vs + (dd * 32 + r) * VST + q * 16 + 8 * h);
;         O[dd] = MFMA32(vv, pf[q], O[dd]);
;       }
;     }
;     {
;       constexpr int NPV = (DV / 32) * 4;
;       __builtin_amdgcn_sched_group_barrier(0x100, 2, 0);
; #pragma unroll
;       for (int q = 0; q < NPV - 2; ++q) { __builtin_amdgcn_sched_group_barrier(0x008, 1, 0); __builtin_amdgcn_sched_group_barrier(0x100, 1, 0); }
;       __builtin_amdgcn_sched_group_barrier(0x008, 6, 0);
;     }
;     __builtin_amdgcn_s_setprio(0);
.LBB0_446:
	s_add_i32 s12, s12, 64
	v_exp_f32_e32 v64, v64
	v_exp_f32_e32 v65, v65
	v_exp_f32_e32 v66, v66
	v_exp_f32_e32 v67, v67
	v_exp_f32_e32 v68, v68
	v_exp_f32_e32 v69, v69
	v_exp_f32_e32 v70, v70
	v_exp_f32_e32 v71, v71
	v_cvt_pk_bf16_f32 v64, v64, v65
	v_cvt_pk_bf16_f32 v65, v66, v67
	v_cvt_pk_bf16_f32 v66, v68, v69
	v_cvt_pk_bf16_f32 v67, v70, v71
	v_mov_b64_e32 v[232:233], s[48:49]
	v_mov_b64_e32 v[234:235], s[50:51]
	s_setprio 1
	s_waitcnt lgkmcnt(0)
	v_mfma_f32_32x32x16_bf16 v[48:63], v[200:203], v[64:67], v[48:63]
	v_exp_f32_e32 v68, v72
	v_exp_f32_e32 v69, v73
	v_exp_f32_e32 v70, v74
	v_exp_f32_e32 v71, v75
	v_mfma_f32_32x32x16_bf16 v[32:47], v[204:207], v[64:67], v[32:47]
	v_cvt_pk_bf16_f32 v68, v68, v69
	v_cvt_pk_bf16_f32 v69, v70, v71
	v_exp_f32_e32 v72, v76
	v_exp_f32_e32 v73, v77
	v_exp_f32_e32 v74, v78
	v_mfma_f32_32x32x16_bf16 v[0:15], v[232:235], v[64:67], v[0:15]
	v_exp_f32_e32 v75, v79
	v_cvt_pk_bf16_f32 v70, v72, v73
	v_cvt_pk_bf16_f32 v71, v74, v75
	s_nop 0
	s_nop 0
	v_mfma_f32_32x32x16_bf16 v[48:63], v[208:211], v[68:71], v[48:63]
	v_exp_f32_e32 v72, v80
	v_exp_f32_e32 v73, v81
	v_exp_f32_e32 v74, v82
	v_exp_f32_e32 v75, v83
	v_mfma_f32_32x32x16_bf16 v[32:47], v[212:215], v[68:71], v[32:47]
	v_cvt_pk_bf16_f32 v72, v72, v73
	v_cvt_pk_bf16_f32 v73, v74, v75
	v_exp_f32_e32 v76, v84
	v_exp_f32_e32 v77, v85
	v_exp_f32_e32 v78, v86
	v_mfma_f32_32x32x16_bf16 v[0:15], v[232:235], v[68:71], v[0:15]
	v_exp_f32_e32 v79, v87
	v_cvt_pk_bf16_f32 v74, v76, v77
	v_cvt_pk_bf16_f32 v75, v78, v79
	s_nop 0
	s_nop 0
	v_mfma_f32_32x32x16_bf16 v[48:63], v[216:219], v[72:75], v[48:63]
	v_exp_f32_e32 v76, v88
	v_exp_f32_e32 v77, v89
	v_exp_f32_e32 v78, v90
	v_exp_f32_e32 v79, v91
	v_mfma_f32_32x32x16_bf16 v[32:47], v[220:223], v[72:75], v[32:47]
	v_cvt_pk_bf16_f32 v76, v76, v77
	v_cvt_pk_bf16_f32 v77, v78, v79
	v_exp_f32_e32 v80, v92
	v_exp_f32_e32 v81, v93
	v_exp_f32_e32 v82, v94
	v_mfma_f32_32x32x16_bf16 v[0:15], v[232:235], v[72:75], v[0:15]
	v_exp_f32_e32 v83, v95
	v_cvt_pk_bf16_f32 v78, v80, v81
	v_cvt_pk_bf16_f32 v79, v82, v83
	s_nop 0
	s_nop 0
	v_mfma_f32_32x32x16_bf16 v[48:63], v[224:227], v[76:79], v[48:63]
	v_mfma_f32_32x32x16_bf16 v[32:47], v[228:231], v[76:79], v[32:47]
	v_mfma_f32_32x32x16_bf16 v[0:15], v[232:235], v[76:79], v[0:15]
	s_setprio 0
	s_mov_b64 s[10:11], 0x4000
	v_lshl_add_u64 v[130:131], v[130:131], 0, s[56:57]
	v_lshl_add_u64 v[132:133], v[132:133], 0, s[56:57]
	v_lshl_add_u64 v[134:135], v[134:135], 0, s[10:11]
	s_andn2_b64 vcc, exec, s[8:9]
	v_lshl_add_u64 v[136:137], v[136:137], 0, s[10:11]
	s_cbranch_vccz .LBB0_451

; #define MFMA32(a, b, c) __builtin_amdgcn_mfma_f32_32x32x16_bf16((a), (b), (c), 0, 0, 0)
; DI float xmax32(float x) { auto t = __builtin_amdgcn_permlane32_swap(__float_as_uint(x), __float_as_uint(x), false, false); return fmaxf(__uint_as_float(t[0]), __uint_as_float(t[1])); }
; template <int DK, int DV>
; DI void attn_map(f32x16 (&O)[DV / 32], float& lsum, const u16* qrow, const u16* K1, int ldk1, const u16* K2, int ldk2, const u16* Vt, int nkeys, char* smem) {
;     ...
;     f32x16 s[2];
;     __builtin_amdgcn_s_setprio(1);
; #pragma unroll
;     for (int j = 0; j < 2; ++j) {
; #pragma unroll
;       for (int ks = 0; ks < DK / 16; ++ks) {
;         bf16x8 kf = *(const bf16x8*)(Ks + (j * 32 + r) * KST + ks * 16 + 8 * h);
;         s[j] = (ks == 0) ? MFMA32(kf, qf[ks], negm) : MFMA32(kf, qf[ks], s[j]);
;       }
;     }
;     {
;       constexpr int NQK = 2 * (DK / 16);
;       __builtin_amdgcn_sched_group_barrier(0x100, 2, 0);
; #pragma unroll
;       for (int q = 0; q < NQK - 2; ++q) { __builtin_amdgcn_sched_group_barrier(0x008, 1, 0); __builtin_amdgcn_sched_group_barrier(0x100, 1, 0); }
;       __builtin_amdgcn_sched_group_barrier(0x008, 2, 0);
;     }
;     __builtin_amdgcn_s_setprio(0);
;     float mx0 = fmaxf(fmaxf(s[0][0], s[0][1]), s[0][2]), mx1 = fmaxf(fmaxf(s[1][0], s[1][1]), s[1][2]);
; #pragma unroll
;     for (int i = 3; i < 15; i += 2) { mx0 = fmaxf(fmaxf(mx0, s[0][i]), s[0][i + 1]); mx1 = fmaxf(fmaxf(mx1, s[1][i]), s[1][i + 1]); }
;     float mx = fmaxf(fmaxf(mx0, mx1), fmaxf(s[0][15], s[1][15]));
;     mx = xmax32(mx);
;     const bool first = (k0 == 0);
;     if (first || __any(mx > 6.f)) {
;       float dl = first ? mx : fmaxf(mx, 0.f);
;       float alpha = __builtin_amdgcn_exp2f(-dl);
; #pragma unroll
;       for (int i = 0; i < 16; ++i) { negm[i] -= dl; lacc[i] *= alpha; }
; #pragma unroll
;       for (int dd = 0; dd < DV / 32; ++dd)
; #pragma unroll
;         for (int i = 0; i < 16; ++i) O[dd][i] *= alpha;
; #pragma unroll
;       for (int j = 0; j < 2; ++j)
; #pragma unroll
;         for (int i = 0; i < 16; ++i) s[j][i] -= dl;
;     }
.LBB0_449:
	s_setprio 1
	ds_read_b128 v[200:203], v143
	ds_read_b128 v[204:207], v143 offset:32
	ds_read_b128 v[208:211], v143 offset:64
	ds_read_b128 v[212:215], v143 offset:96
	ds_read_b128 v[216:219], v143 offset:4608
	ds_read_b128 v[220:223], v143 offset:4640
	ds_read_b128 v[224:227], v143 offset:4672
	ds_read_b128 v[228:231], v143 offset:4704
	s_waitcnt lgkmcnt(7)
	v_mfma_f32_32x32x16_bf16 v[64:79], v[200:203], v[96:99], v[16:31]
	s_waitcnt lgkmcnt(6)
	v_mfma_f32_32x32x16_bf16 v[64:79], v[204:207], v[100:103], v[64:79]
	s_waitcnt lgkmcnt(5)
	v_mfma_f32_32x32x16_bf16 v[64:79], v[208:211], v[104:107], v[64:79]
	s_waitcnt lgkmcnt(4)
	v_mfma_f32_32x32x16_bf16 v[64:79], v[212:215], v[108:111], v[64:79]
	s_waitcnt lgkmcnt(3)
	v_mfma_f32_32x32x16_bf16 v[80:95], v[216:219], v[96:99], v[16:31]
	s_waitcnt lgkmcnt(2)
	v_mfma_f32_32x32x16_bf16 v[80:95], v[220:223], v[100:103], v[80:95]
	s_waitcnt lgkmcnt(1)
	v_mfma_f32_32x32x16_bf16 v[80:95], v[224:227], v[104:107], v[80:95]
	s_waitcnt lgkmcnt(0)
	v_mfma_f32_32x32x16_bf16 v[80:95], v[228:231], v[108:111], v[80:95]
	s_setprio 0
	ds_read_b128 v[200:203], v143 offset:9216
	ds_read_b128 v[204:207], v143 offset:13824
	ds_read_b128 v[208:211], v143 offset:9248
	ds_read_b128 v[212:215], v143 offset:13856
	ds_read_b128 v[216:219], v143 offset:9280
	ds_read_b128 v[220:223], v143 offset:13888
	ds_read_b128 v[224:227], v143 offset:9312
	ds_read_b128 v[228:231], v143 offset:13920
	s_nop 0
	v_max3_f32 v144, v64, v65, v66
	s_nop 8
	v_max3_f32 v145, v80, v81, v82
	v_max3_f32 v144, v144, v67, v68
	v_max3_f32 v145, v145, v83, v84
	v_max3_f32 v144, v144, v69, v70
	v_max3_f32 v145, v145, v85, v86
	v_max3_f32 v144, v144, v71, v72
	v_max3_f32 v145, v145, v87, v88
	v_max3_f32 v144, v144, v73, v74
	v_max3_f32 v145, v145, v89, v90
	v_max3_f32 v144, v144, v75, v76
	v_max3_f32 v145, v145, v91, v92
	v_max_f32_e32 v146, v95, v95
	v_max_f32_e32 v147, v79, v79
	v_max3_f32 v144, v144, v77, v78
	v_max3_f32 v145, v145, v93, v94
	v_max_f32_e32 v146, v147, v146
	v_max3_f32 v144, v144, v145, v146
	v_mov_b32_e32 v145, v144
	s_nop 1
	v_permlane32_swap_b32_e32 v144, v145
	v_max_f32_e32 v145, v145, v145
	v_max_f32_e32 v144, v144, v144
	v_max_f32_e32 v144, v144, v145
	v_cmp_lt_f32_e32 vcc, s45, v144
	s_cbranch_vccz .LBB0_446
	v_max_f32_e32 v144, v144, v144
	v_max_f32_e32 v145, 0, v144
	v_exp_f32_e64 v144, -v145
	v_sub_f32_e32 v31, v31, v145
	v_sub_f32_e32 v30, v30, v145
	v_sub_f32_e32 v29, v29, v145
	v_pk_mul_f32 v[62:63], v[62:63], v[144:145] op_sel_hi:[1,0]
	v_pk_mul_f32 v[60:61], v[60:61], v[144:145] op_sel_hi:[1,0]
	v_pk_mul_f32 v[58:59], v[58:59], v[144:145] op_sel_hi:[1,0]
	v_pk_mul_f32 v[56:57], v[56:57], v[144:145] op_sel_hi:[1,0]
	v_pk_mul_f32 v[54:55], v[54:55], v[144:145] op_sel_hi:[1,0]
	v_pk_mul_f32 v[52:53], v[52:53], v[144:145] op_sel_hi:[1,0]
	v_pk_mul_f32 v[50:51], v[50:51], v[144:145] op_sel_hi:[1,0]
	v_pk_mul_f32 v[48:49], v[48:49], v[144:145] op_sel_hi:[1,0]
	v_pk_mul_f32 v[46:47], v[46:47], v[144:145] op_sel_hi:[1,0]
	v_pk_mul_f32 v[44:45], v[44:45], v[144:145] op_sel_hi:[1,0]
	v_pk_mul_f32 v[42:43], v[42:43], v[144:145] op_sel_hi:[1,0]
	v_pk_mul_f32 v[40:41], v[40:41], v[144:145] op_sel_hi:[1,0]
	v_pk_mul_f32 v[38:39], v[38:39], v[144:145] op_sel_hi:[1,0]
	v_pk_mul_f32 v[36:37], v[36:37], v[144:145] op_sel_hi:[1,0]
	v_pk_mul_f32 v[34:35], v[34:35], v[144:145] op_sel_hi:[1,0]
	v_pk_mul_f32 v[32:33], v[32:33], v[144:145] op_sel_hi:[1,0]
	v_sub_f32_e32 v28, v28, v145
	v_sub_f32_e32 v27, v27, v145
	v_sub_f32_e32 v26, v26, v145
	v_sub_f32_e32 v25, v25, v145
	v_sub_f32_e32 v24, v24, v145
	v_sub_f32_e32 v23, v23, v145
	v_sub_f32_e32 v22, v22, v145
	v_sub_f32_e32 v21, v21, v145
	v_sub_f32_e32 v20, v20, v145
	v_sub_f32_e32 v19, v19, v145
	v_sub_f32_e32 v18, v18, v145
	v_sub_f32_e32 v17, v17, v145
	v_sub_f32_e32 v16, v16, v145
	v_sub_f32_e32 v64, v64, v145
	v_sub_f32_e32 v65, v65, v145
	v_sub_f32_e32 v66, v66, v145
	v_sub_f32_e32 v67, v67, v145
	v_sub_f32_e32 v68, v68, v145
	v_sub_f32_e32 v69, v69, v145
	v_sub_f32_e32 v70, v70, v145
	v_sub_f32_e32 v71, v71, v145
	v_sub_f32_e32 v72, v72, v145
	v_sub_f32_e32 v73, v73, v145
	v_sub_f32_e32 v74, v74, v145
	v_sub_f32_e32 v75, v75, v145
	v_sub_f32_e32 v76, v76, v145
	v_sub_f32_e32 v77, v77, v145
	v_sub_f32_e32 v78, v78, v145
	v_sub_f32_e32 v79, v79, v145
	v_sub_f32_e32 v80, v80, v145
	v_sub_f32_e32 v81, v81, v145
	v_sub_f32_e32 v82, v82, v145
	v_sub_f32_e32 v83, v83, v145
	v_sub_f32_e32 v84, v84, v145
	v_sub_f32_e32 v85, v85, v145
	v_sub_f32_e32 v86, v86, v145
	v_sub_f32_e32 v87, v87, v145
	v_sub_f32_e32 v88, v88, v145
	v_sub_f32_e32 v89, v89, v145
	v_sub_f32_e32 v90, v90, v145
	v_sub_f32_e32 v91, v91, v145
	v_sub_f32_e32 v92, v92, v145
	v_sub_f32_e32 v93, v93, v145
	v_sub_f32_e32 v94, v94, v145
	v_sub_f32_e32 v95, v95, v145
	v_pk_mul_f32 v[14:15], v[14:15], v[144:145] op_sel_hi:[1,0]
	v_pk_mul_f32 v[12:13], v[12:13], v[144:145] op_sel_hi:[1,0]
	v_pk_mul_f32 v[10:11], v[10:11], v[144:145] op_sel_hi:[1,0]
	v_pk_mul_f32 v[8:9], v[8:9], v[144:145] op_sel_hi:[1,0]
	v_pk_mul_f32 v[6:7], v[6:7], v[144:145] op_sel_hi:[1,0]
	v_pk_mul_f32 v[4:5], v[4:5], v[144:145] op_sel_hi:[1,0]
	v_pk_mul_f32 v[2:3], v[2:3], v[144:145] op_sel_hi:[1,0]
	v_pk_mul_f32 v[0:1], v[0:1], v[144:145] op_sel_hi:[1,0]
	s_branch .LBB0_446
